# counted vmcnt(3) in the gate/up 128x64 pieces K-loops so the distance-2 register prefetch stays in flight
# speedup vs baseline: 1.1379x; 1.0091x over previous
.LBB0_17:
	s_cmp_gt_u32 s13, 29
	s_cselect_b64 s[8:9], -1, 0
	s_and_b64 vcc, exec, s[8:9]
	v_lshl_add_u64 v[48:49], v[44:45], 0, v[0:1]
	v_lshl_add_u64 v[46:47], v[42:43], 0, v[0:1]
	s_waitcnt vmcnt(3)
	ds_write_b128 v54, v[10:13]
	ds_write_b128 v54, v[18:21] offset:8192
	ds_write_b128 v54, v[14:17] offset:32768
	ds_write_b128 v54, v[14:17] offset:40960
	s_waitcnt lgkmcnt(0)
	s_barrier
	s_cbranch_vccnz .LBB0_19
	v_add_co_u32_e32 v14, vcc, 0x40000, v48
	s_nop 1
	v_addc_co_u32_e32 v15, vcc, 0, v49, vcc
	global_load_dwordx4 v[10:13], v[48:49], off offset:256
	global_load_dwordx4 v[18:21], v[14:15], off offset:256
	s_nop 0
	global_load_dwordx4 v[14:17], v[46:47], off offset:256
.LBB0_19:
	ds_read_b128 v[60:63], v55 offset:32768
	ds_read_b128 v[64:67], v57
	ds_read_b128 v[68:71], v57 offset:2048
	ds_read_b128 v[72:75], v56 offset:32768
	s_waitcnt lgkmcnt(2)
	v_mfma_f32_16x16x32_bf16 v[26:29], v[60:63], v[64:67], v[26:29]
	s_waitcnt lgkmcnt(1)
	v_mfma_f32_16x16x32_bf16 v[22:25], v[60:63], v[68:71], v[22:25]
	ds_read_b128 v[64:67], v57 offset:4096
	ds_read_b128 v[68:71], v57 offset:6144
	s_waitcnt lgkmcnt(1)
	v_mfma_f32_16x16x32_bf16 v[64:67], v[60:63], v[64:67], v[6:9]
	s_waitcnt lgkmcnt(0)
	v_mfma_f32_16x16x32_bf16 v[2:5], v[60:63], v[68:71], v[2:5]
	s_nop 0
	ds_read_b128 v[6:9], v58
	ds_read_b128 v[60:63], v58 offset:2048
	ds_read_b128 v[68:71], v58 offset:4096
	ds_read_b128 v[76:79], v58 offset:6144
	s_cmp_eq_u64 s[8:9], 0
	s_cbranch_scc1 .Lpc_u_w2s
	s_waitcnt vmcnt(0)
	s_branch .Lpc_u_w2d
.Lpc_u_w2s:
	s_waitcnt vmcnt(3)
.Lpc_u_w2d:
	ds_write_b128 v54, v[34:37] offset:16384
	s_waitcnt lgkmcnt(4)
	v_mfma_f32_16x16x32_bf16 v[26:29], v[72:75], v[6:9], v[26:29]
	ds_write_b128 v54, v[38:41] offset:24576
	ds_write_b128 v54, v[30:33] offset:49152
	ds_write_b128 v54, v[30:33] offset:57344
	s_waitcnt lgkmcnt(0)
	s_barrier
	v_mfma_f32_16x16x32_bf16 v[6:9], v[72:75], v[60:63], v[22:25]
	v_mfma_f32_16x16x32_bf16 v[22:25], v[72:75], v[68:71], v[64:67]
	v_mfma_f32_16x16x32_bf16 v[2:5], v[72:75], v[76:79], v[2:5]
	s_cmp_gt_u32 s13, 28
	s_cbranch_scc1 .LBB0_16
	v_add_co_u32_e32 v30, vcc, 0x40000, v48
	s_nop 1
	v_addc_co_u32_e32 v31, vcc, 0, v49, vcc
	global_load_dwordx4 v[34:37], v[48:49], off offset:384
	global_load_dwordx4 v[38:41], v[30:31], off offset:384
	s_nop 0
	global_load_dwordx4 v[30:33], v[46:47], off offset:384
	s_branch .LBB0_16

.LBB0_77:
	s_cmp_gt_u32 s11, 29
	s_cselect_b64 s[6:7], -1, 0
	s_and_b64 vcc, exec, s[6:7]
	v_lshl_add_u64 v[48:49], v[44:45], 0, v[0:1]
	v_lshl_add_u64 v[46:47], v[42:43], 0, v[0:1]
	s_cmp_lg_u32 s11, 0
	s_cbranch_scc1 .Lpc_g_w1s
	s_waitcnt vmcnt(0)
	s_branch .Lpc_g_w1d

.Lpc_g_w1d:
	ds_write_b128 v54, v[2:5]
	ds_write_b128 v54, v[10:13] offset:8192
	ds_write_b128 v54, v[6:9] offset:32768
	ds_write_b128 v54, v[6:9] offset:40960
	s_waitcnt lgkmcnt(0)
	s_barrier
	s_cbranch_vccnz .LBB0_79
	v_add_co_u32_e32 v6, vcc, 0x40000, v48
	s_nop 1
	v_addc_co_u32_e32 v7, vcc, 0, v49, vcc
	global_load_dwordx4 v[2:5], v[48:49], off offset:256
	global_load_dwordx4 v[10:13], v[6:7], off offset:256
	s_nop 0
	global_load_dwordx4 v[6:9], v[46:47], off offset:256
.LBB0_79:
	ds_read_b128 v[60:63], v55 offset:32768
	ds_read_b128 v[64:67], v57
	ds_read_b128 v[68:71], v57 offset:2048
	ds_read_b128 v[72:75], v56 offset:32768
	s_waitcnt lgkmcnt(2)
	v_mfma_f32_16x16x32_bf16 v[26:29], v[60:63], v[64:67], v[26:29]
	s_waitcnt lgkmcnt(1)
	v_mfma_f32_16x16x32_bf16 v[30:33], v[60:63], v[68:71], v[30:33]
	ds_read_b128 v[64:67], v57 offset:4096
	ds_read_b128 v[68:71], v57 offset:6144
	s_waitcnt lgkmcnt(1)
	v_mfma_f32_16x16x32_bf16 v[64:67], v[60:63], v[64:67], v[38:41]
	s_waitcnt lgkmcnt(0)
	v_mfma_f32_16x16x32_bf16 v[60:63], v[60:63], v[68:71], v[34:37]
	s_nop 2
	ds_read_b128 v[34:37], v58
	ds_read_b128 v[68:71], v58 offset:2048
	s_waitcnt lgkmcnt(1)
	v_mfma_f32_16x16x32_bf16 v[38:41], v[72:75], v[34:37], v[26:29]
	s_nop 2
	ds_read_b128 v[26:29], v58 offset:4096
	ds_read_b128 v[76:79], v58 offset:6144
	s_cmp_eq_u64 s[6:7], 0
	s_cbranch_scc1 .Lpc_g_w2s
	s_waitcnt vmcnt(0)
	s_branch .Lpc_g_w2d

.Lpc_g_w2d:
	ds_write_b128 v54, v[18:21] offset:16384
	ds_write_b128 v54, v[22:25] offset:24576
	ds_write_b128 v54, v[14:17] offset:49152
	ds_write_b128 v54, v[14:17] offset:57344
	s_waitcnt lgkmcnt(6)
	v_mfma_f32_16x16x32_bf16 v[30:33], v[72:75], v[68:71], v[30:33]
	s_waitcnt lgkmcnt(0)
	s_barrier
	v_mfma_f32_16x16x32_bf16 v[34:37], v[72:75], v[26:29], v[64:67]
	v_mfma_f32_16x16x32_bf16 v[26:29], v[72:75], v[76:79], v[60:63]
	s_cmp_gt_u32 s11, 28
	s_cbranch_scc1 .LBB0_76
	v_add_co_u32_e32 v14, vcc, 0x40000, v48
	s_nop 1
	v_addc_co_u32_e32 v15, vcc, 0, v49, vcc
	global_load_dwordx4 v[18:21], v[48:49], off offset:384
	global_load_dwordx4 v[22:25], v[14:15], off offset:384
	s_nop 0
	global_load_dwordx4 v[14:17], v[46:47], off offset:384
	s_branch .LBB0_76
